# SiLU gates and RMSNorm scale in F2 epilogue and GLA mix build: the 68 full-range IEEE division sequences per trip become N * v_rcp_f32(D) (f32, denominators >= 1)
# speedup vs baseline: 1.0638x; 1.0072x over previous
.LBB0_308:
	s_and_b32 s20, s11, 1
	s_lshl_b32 s0, s20, 2
	s_add_i32 s0, s8, s0
	s_lshl_b64 s[6:7], s[0:1], 23
	s_and_b32 s0, s10, 0xfffff000
	s_lshr_b32 s21, s11, 1
	s_waitcnt lgkmcnt(0)
	s_barrier
	s_waitcnt vmcnt(4)
	ds_write_b128 v92, v[14:17]
	ds_write_b128 v92, v[30:33] offset:33792
	ds_write_b128 v92, v[10:13] offset:16
	ds_write_b128 v92, v[26:29] offset:33808
	ds_write_b128 v92, v[6:9] offset:32
	ds_write_b128 v92, v[22:25] offset:33824
	ds_write_b128 v92, v[2:5] offset:48
	ds_write_b128 v92, v[18:21] offset:33840
	v_or_b32_e32 v2, s0, v90
	v_and_or_b32 v82, s21, 63, v2
	v_ashrrev_i32_e32 v83, 31, v82
	v_lshl_add_u64 v[2:3], v[76:77], 0, s[6:7]
	v_lshlrev_b64 v[4:5], 7, v[82:83]
	v_lshl_add_u64 v[4:5], v[2:3], 0, v[4:5]
	s_waitcnt lgkmcnt(0)
	s_barrier
	v_mov_b32_e32 v70, v120
	v_mov_b32_e32 v71, v121
	v_mov_b32_e32 v72, v122
	v_mov_b32_e32 v73, v123
	v_mov_b32_e32 v58, v124
	v_mov_b32_e32 v59, v125
	v_mov_b32_e32 v60, v126
	v_mov_b32_e32 v61, v127
	v_mov_b32_e32 v42, v128
	v_mov_b32_e32 v43, v129
	v_mov_b32_e32 v44, v130
	v_mov_b32_e32 v45, v131
	v_mov_b32_e32 v34, v132
	v_mov_b32_e32 v35, v133
	v_mov_b32_e32 v36, v134
	v_mov_b32_e32 v37, v135
	v_or_b32_e32 v84, 0x400, v82
	v_ashrrev_i32_e32 v85, 31, v84
	s_add_i32 s0, s11, s3
	v_lshlrev_b64 v[4:5], 7, v[84:85]
	v_or_b32_e32 v80, 0x800, v82
	s_cmpk_lt_i32 s0, 0x800
	v_lshl_add_u64 v[4:5], v[2:3], 0, v[4:5]
	v_ashrrev_i32_e32 v81, 31, v80
	s_cselect_b64 s[6:7], -1, 0
	v_lshlrev_b64 v[4:5], 7, v[80:81]
	v_or_b32_e32 v78, 0xc00, v82
	s_and_b64 s[22:23], s[6:7], exec
	v_lshl_add_u64 v[4:5], v[2:3], 0, v[4:5]
	v_ashrrev_i32_e32 v79, 31, v78
	s_cselect_b32 s11, s0, s11
	s_and_b32 s80, s11, 1
	s_lshl_b32 s80, s80, 2
	s_add_i32 s80, s8, s80
	s_mov_b32 s81, 0
	s_lshl_b64 s[80:81], s[80:81], 23
	s_lshl_b32 s82, s11, 5
	s_and_b32 s82, s82, 0xfffff000
	s_lshr_b32 s83, s11, 1
	s_and_b32 s83, s83, 63
	s_or_b32 s82, s82, s83
	v_or_b32_e32 v116, s82, v90
	v_lshlrev_b32_e32 v116, 7, v116
	v_mov_b32_e32 v117, 0
	v_lshl_add_u64 v[116:117], v[76:77], 0, v[116:117]
	v_lshl_add_u64 v[116:117], v[116:117], 0, s[80:81]
	global_load_dwordx4 v[120:123], v[116:117], off
	v_lshl_add_u64 v[116:117], v[116:117], 0, s[84:85]
	global_load_dwordx4 v[124:127], v[116:117], off
	v_lshl_add_u64 v[116:117], v[116:117], 0, s[84:85]
	global_load_dwordx4 v[128:131], v[116:117], off
	v_lshl_add_u64 v[116:117], v[116:117], 0, s[84:85]
	global_load_dwordx4 v[132:135], v[116:117], off
	v_lshlrev_b64 v[4:5], 7, v[78:79]
	s_lshl_b32 s21, s11, 5
	v_lshl_add_u64 v[2:3], v[2:3], 0, v[4:5]
	s_andn2_b32 s21, s21, 63
	v_or_b32_e32 v2, s21, v1
	v_ashrrev_i32_e32 v3, 31, v2
	s_lshl_b32 s11, s11, 8
	v_lshlrev_b64 v[2:3], 9, v[2:3]
	s_and_b32 s11, s11, 0x100
	v_or_b32_e32 v2, s11, v2
	v_or_b32_e32 v2, v2, v74
	v_lshlrev_b64 v[2:3], 1, v[2:3]
	v_lshl_add_u64 v[38:39], s[14:15], 0, v[2:3]
	v_lshl_add_u64 v[40:41], s[12:13], 0, v[2:3]
	global_load_dwordx4 v[2:5], v[38:39], off offset:48
	global_load_dwordx4 v[6:9], v[38:39], off offset:32
	global_load_dwordx4 v[10:13], v[38:39], off offset:16
	global_load_dwordx4 v[14:17], v[38:39], off
	global_load_dwordx4 v[18:21], v[40:41], off offset:48
	global_load_dwordx4 v[22:25], v[40:41], off offset:32
	global_load_dwordx4 v[26:29], v[40:41], off offset:16
	global_load_dwordx4 v[30:33], v[40:41], off
	ds_read_b64_tr_b16 v[40:41], v93 offset:2112
	ds_read_b64_tr_b16 v[38:39], v93
	ds_read_b64_tr_b16 v[46:47], v93 offset:8
	ds_read_b64_tr_b16 v[48:49], v93 offset:2120
	ds_read_b128 v[50:53], v94
	ds_read_b128 v[62:65], v94 offset:4352
	ds_read_b128 v[86:89], v94 offset:8704
	ds_read_b128 v[100:103], v94 offset:13056
	s_waitcnt lgkmcnt(3)
	v_mfma_f32_16x16x32_bf16 v[54:57], v[38:41], v[50:53], 0
	v_lshlrev_b64 v[82:83], 11, v[82:83]
	s_add_i32 s10, s10, s9
	s_mov_b32 s11, s0
	v_mfma_f32_16x16x32_bf16 v[50:53], v[46:49], v[50:53], 0
	v_lshlrev_b32_e32 v95, 16, v70
	s_waitcnt lgkmcnt(2)
	v_mfma_f32_16x16x32_bf16 v[66:69], v[38:41], v[62:65], 0
	v_and_b32_e32 v70, 0xffff0000, v70
	v_mfma_f32_16x16x32_bf16 v[62:65], v[46:49], v[62:65], 0
	s_waitcnt lgkmcnt(1)
	v_mfma_f32_16x16x32_bf16 v[96:99], v[38:41], v[86:89], 0
	v_mfma_f32_16x16x32_bf16 v[86:89], v[46:49], v[86:89], 0
	s_waitcnt lgkmcnt(0)
	v_mfma_f32_16x16x32_bf16 v[38:41], v[38:41], v[100:103], 0
	v_mfma_f32_16x16x32_bf16 v[46:49], v[46:49], v[100:103], 0
	ds_read_b64_tr_b16 v[100:101], v93 offset:16896
	ds_read_b64_tr_b16 v[102:103], v93 offset:19008
	ds_read_b64_tr_b16 v[104:105], v93 offset:16904
	ds_read_b64_tr_b16 v[106:107], v93 offset:19016
	ds_read_b128 v[108:111], v94 offset:64
	s_waitcnt lgkmcnt(0)
	v_mfma_f32_16x16x32_bf16 v[54:57], v[100:103], v[108:111], v[54:57]
	v_mfma_f32_16x16x32_bf16 v[50:53], v[104:107], v[108:111], v[50:53]
	ds_read_b128 v[108:111], v94 offset:4416
	s_waitcnt lgkmcnt(0)
	v_mfma_f32_16x16x32_bf16 v[66:69], v[100:103], v[108:111], v[66:69]
	v_mfma_f32_16x16x32_bf16 v[62:65], v[104:107], v[108:111], v[62:65]
	ds_read_b128 v[108:111], v94 offset:8768
	s_waitcnt lgkmcnt(0)
	v_mfma_f32_16x16x32_bf16 v[96:99], v[100:103], v[108:111], v[96:99]
	v_mfma_f32_16x16x32_bf16 v[86:89], v[104:107], v[108:111], v[86:89]
	ds_read_b128 v[108:111], v94 offset:13120
	s_waitcnt lgkmcnt(0)
	v_mfma_f32_16x16x32_bf16 v[38:41], v[100:103], v[108:111], v[38:41]
	v_mfma_f32_16x16x32_bf16 v[46:49], v[104:107], v[108:111], v[46:49]
	ds_read_b64_tr_b16 v[100:101], v93 offset:33792
	ds_read_b64_tr_b16 v[102:103], v93 offset:35904
	ds_read_b64_tr_b16 v[104:105], v93 offset:33800
	ds_read_b64_tr_b16 v[106:107], v93 offset:35912
	ds_read_b128 v[108:111], v94 offset:128
	s_waitcnt lgkmcnt(0)
	v_mfma_f32_16x16x32_bf16 v[54:57], v[100:103], v[108:111], v[54:57]
	v_mfma_f32_16x16x32_bf16 v[50:53], v[104:107], v[108:111], v[50:53]
	ds_read_b128 v[108:111], v94 offset:4480
	s_waitcnt lgkmcnt(0)
	v_mfma_f32_16x16x32_bf16 v[66:69], v[100:103], v[108:111], v[66:69]
	v_mfma_f32_16x16x32_bf16 v[62:65], v[104:107], v[108:111], v[62:65]
	ds_read_b128 v[108:111], v94 offset:8832
	s_waitcnt lgkmcnt(0)
	v_mfma_f32_16x16x32_bf16 v[96:99], v[100:103], v[108:111], v[96:99]
	v_mfma_f32_16x16x32_bf16 v[86:89], v[104:107], v[108:111], v[86:89]
	ds_read_b128 v[108:111], v94 offset:13184
	s_waitcnt lgkmcnt(0)
	v_mfma_f32_16x16x32_bf16 v[38:41], v[100:103], v[108:111], v[38:41]
	v_mfma_f32_16x16x32_bf16 v[100:103], v[104:107], v[108:111], v[46:49]
	s_nop 2
	ds_read_b64_tr_b16 v[46:47], v93 offset:50688
	ds_read_b64_tr_b16 v[48:49], v93 offset:52800
	ds_read_b64_tr_b16 v[104:105], v93 offset:50696
	ds_read_b64_tr_b16 v[106:107], v93 offset:52808
	ds_read_b128 v[108:111], v94 offset:192
	s_waitcnt lgkmcnt(0)
	v_mfma_f32_16x16x32_bf16 v[112:115], v[46:49], v[108:111], v[54:57]
	v_mfma_f32_16x16x32_bf16 v[108:111], v[104:107], v[108:111], v[50:53]
	s_nop 2
	ds_read_b128 v[50:53], v94 offset:4544
	s_waitcnt lgkmcnt(0)
	v_mfma_f32_16x16x32_bf16 v[66:69], v[46:49], v[50:53], v[66:69]
	v_mfma_f32_16x16x32_bf16 v[62:65], v[104:107], v[50:53], v[62:65]
	ds_read_b128 v[50:53], v94 offset:8896
	s_nop 5
	v_pk_mul_f32 v[66:67], v[66:67], s[4:5] op_sel_hi:[1,0]
	v_pk_mul_f32 v[68:69], v[68:69], s[4:5] op_sel_hi:[1,0]
	s_waitcnt lgkmcnt(0)
	v_mfma_f32_16x16x32_bf16 v[54:57], v[46:49], v[50:53], v[96:99]
	s_nop 2
	v_mul_f32_e32 v98, 0xbfb8aa3b, v95
	v_mul_f32_e32 v99, 0xbfb8aa3b, v70
	v_mfma_f32_16x16x32_bf16 v[50:53], v[104:107], v[50:53], v[86:89]
	v_exp_f32_e32 v98, v98
	v_exp_f32_e32 v99, v99
	v_pk_mul_f32 v[96:97], v[112:113], s[4:5] op_sel_hi:[1,0]
	ds_read_b128 v[86:89], v94 offset:13248
	s_waitcnt lgkmcnt(0)
	v_mfma_f32_16x16x32_bf16 v[46:49], v[46:49], v[86:89], v[38:41]
	v_add_f32_e64 v98, v98, 1.0
	v_add_f32_e64 v99, v99, 1.0
	v_pk_mul_f32 v[62:63], v[62:63], s[4:5] op_sel_hi:[1,0]
	v_pk_mul_f32 v[64:65], v[64:65], s[4:5] op_sel_hi:[1,0]
	v_mfma_f32_16x16x32_bf16 v[38:41], v[104:107], v[86:89], v[100:103]
	v_lshl_add_u32 v86, s20, 8, v91
	v_pk_mul_f32 v[88:89], v[114:115], s[4:5] op_sel_hi:[1,0]
	v_ashrrev_i32_e32 v87, 31, v86
	v_pk_mul_f32 v[54:55], v[54:55], s[4:5] op_sel_hi:[1,0]
	v_pk_mul_f32 v[56:57], v[56:57], s[4:5] op_sel_hi:[1,0]
	v_pk_mul_f32 v[50:51], v[50:51], s[4:5] op_sel_hi:[1,0]
	v_rcp_f32_e32 v100, v99
	s_nop 0
	v_mul_f32_e32 v99, v70, v100
	v_pk_mul_f32 v[52:53], v[52:53], s[4:5] op_sel_hi:[1,0]
	s_nop 1
	v_pk_mul_f32 v[38:39], v[38:39], s[4:5] op_sel_hi:[1,0]
	v_pk_mul_f32 v[40:41], v[40:41], s[4:5] op_sel_hi:[1,0]
	v_rcp_f32_e32 v70, v98
	s_nop 0
	v_mul_f32_e32 v98, v95, v70
	v_pk_mul_f32 v[96:97], v[98:99], v[96:97]
	v_lshlrev_b32_e32 v95, 16, v71
	v_and_b32_e32 v71, 0xffff0000, v71
	v_cvt_pk_bf16_f32 v70, v96, v97
	v_mul_f32_e32 v96, 0xbfb8aa3b, v95
	v_mul_f32_e32 v97, 0xbfb8aa3b, v71
	v_exp_f32_e32 v96, v96
	v_exp_f32_e32 v97, v97
	s_nop 0
	v_pk_add_f32 v[96:97], v[96:97], 1.0 op_sel_hi:[1,0]
	s_nop 0
	s_nop 0
	v_rcp_f32_e32 v98, v97
	s_nop 0
	v_mul_f32_e32 v97, v71, v98
	s_nop 0
	v_rcp_f32_e32 v71, v96
	s_nop 0
	v_mul_f32_e32 v96, v95, v71
	v_lshlrev_b32_e32 v95, 16, v72
	v_and_b32_e32 v72, 0xffff0000, v72
	v_mul_f32_e32 v98, 0xbfb8aa3b, v95
	v_mul_f32_e32 v99, 0xbfb8aa3b, v72
	v_exp_f32_e32 v98, v98
	v_exp_f32_e32 v99, v99
	v_pk_mul_f32 v[88:89], v[96:97], v[88:89]
	v_pk_mul_f32 v[96:97], v[108:109], s[4:5] op_sel_hi:[1,0]
	v_cvt_pk_bf16_f32 v71, v88, v89
	v_pk_add_f32 v[98:99], v[98:99], 1.0 op_sel_hi:[1,0]
	v_pk_mul_f32 v[88:89], v[110:111], s[4:5] op_sel_hi:[1,0]
	s_nop 0
	v_rcp_f32_e32 v100, v99
	s_nop 0
	v_mul_f32_e32 v99, v72, v100
	s_nop 0
	v_rcp_f32_e32 v72, v98
	s_nop 0
	v_mul_f32_e32 v98, v95, v72
	v_pk_mul_f32 v[96:97], v[98:99], v[96:97]
	v_lshlrev_b32_e32 v95, 16, v73
	v_and_b32_e32 v73, 0xffff0000, v73
	v_cvt_pk_bf16_f32 v72, v96, v97
	v_mul_f32_e32 v96, 0xbfb8aa3b, v95
	v_mul_f32_e32 v97, 0xbfb8aa3b, v73
	v_exp_f32_e32 v96, v96
	v_exp_f32_e32 v97, v97
	s_nop 0
	v_pk_add_f32 v[96:97], v[96:97], 1.0 op_sel_hi:[1,0]
	s_nop 0
	s_nop 0
	v_rcp_f32_e32 v98, v97
	s_nop 0
	v_mul_f32_e32 v97, v73, v98
	s_nop 0
	v_rcp_f32_e32 v73, v96
	s_nop 0
	v_mul_f32_e32 v96, v95, v73
	v_pk_mul_f32 v[88:89], v[96:97], v[88:89]
	s_nop 0
	v_cvt_pk_bf16_f32 v73, v88, v89
	v_lshl_add_u64 v[88:89], s[18:19], 0, v[82:83]
	v_lshlrev_b64 v[82:83], 1, v[86:87]
	v_lshl_add_u64 v[86:87], v[88:89], 0, v[82:83]
	global_store_dwordx4 v[86:87], v[70:73], off offset:1024
	s_nop 0
	s_nop 0
	v_lshlrev_b32_e32 v72, 16, v58
	v_and_b32_e32 v58, 0xffff0000, v58
	v_mul_f32_e32 v70, 0xbfb8aa3b, v72
	v_mul_f32_e32 v71, 0xbfb8aa3b, v58
	v_exp_f32_e32 v70, v70
	v_exp_f32_e32 v71, v71
	s_nop 0
	v_pk_add_f32 v[70:71], v[70:71], 1.0 op_sel_hi:[1,0]
	s_nop 0
	s_nop 0
	v_rcp_f32_e32 v73, v71
	s_nop 0
	v_mul_f32_e32 v71, v58, v73
	s_nop 0
	v_rcp_f32_e32 v58, v70
	s_nop 0
	v_mul_f32_e32 v70, v72, v58
	v_pk_mul_f32 v[66:67], v[70:71], v[66:67]
	v_lshlrev_b32_e32 v70, 16, v59
	v_and_b32_e32 v59, 0xffff0000, v59
	v_cvt_pk_bf16_f32 v58, v66, v67
	v_mul_f32_e32 v66, 0xbfb8aa3b, v70
	v_mul_f32_e32 v67, 0xbfb8aa3b, v59
	v_exp_f32_e32 v66, v66
	v_exp_f32_e32 v67, v67
	s_nop 0
	v_pk_add_f32 v[66:67], v[66:67], 1.0 op_sel_hi:[1,0]
	s_nop 0
	s_nop 0
	v_rcp_f32_e32 v71, v67
	s_nop 0
	v_mul_f32_e32 v67, v59, v71
	s_nop 0
	v_rcp_f32_e32 v59, v66
	s_nop 0
	v_mul_f32_e32 v66, v70, v59
	v_pk_mul_f32 v[66:67], v[66:67], v[68:69]
	v_lshlrev_b32_e32 v68, 16, v60
	v_and_b32_e32 v60, 0xffff0000, v60
	v_cvt_pk_bf16_f32 v59, v66, v67
	v_mul_f32_e32 v66, 0xbfb8aa3b, v68
	v_mul_f32_e32 v67, 0xbfb8aa3b, v60
	v_exp_f32_e32 v66, v66
	v_exp_f32_e32 v67, v67
	s_nop 0
	v_pk_add_f32 v[66:67], v[66:67], 1.0 op_sel_hi:[1,0]
	s_nop 0
	s_nop 0
	v_rcp_f32_e32 v69, v67
	s_nop 0
	v_mul_f32_e32 v67, v60, v69
	s_nop 0
	v_rcp_f32_e32 v60, v66
	s_nop 0
	v_mul_f32_e32 v66, v68, v60
	v_pk_mul_f32 v[62:63], v[66:67], v[62:63]
	v_lshlrev_b32_e32 v66, 16, v61
	v_and_b32_e32 v61, 0xffff0000, v61
	v_cvt_pk_bf16_f32 v60, v62, v63
	v_mul_f32_e32 v62, 0xbfb8aa3b, v66
	v_mul_f32_e32 v63, 0xbfb8aa3b, v61
	v_exp_f32_e32 v62, v62
	v_exp_f32_e32 v63, v63
	s_nop 0
	v_pk_add_f32 v[62:63], v[62:63], 1.0 op_sel_hi:[1,0]
	s_nop 0
	s_nop 0
	v_rcp_f32_e32 v67, v63
	s_nop 0
	v_mul_f32_e32 v63, v61, v67
	s_nop 0
	v_rcp_f32_e32 v61, v62
	s_nop 0
	v_mul_f32_e32 v62, v66, v61
	v_pk_mul_f32 v[62:63], v[62:63], v[64:65]
	s_nop 0
	v_cvt_pk_bf16_f32 v61, v62, v63
	v_lshlrev_b64 v[62:63], 11, v[84:85]
	v_lshl_add_u64 v[62:63], s[18:19], 0, v[62:63]
	v_lshl_add_u64 v[62:63], v[62:63], 0, v[82:83]
	global_store_dwordx4 v[62:63], v[58:61], off offset:1024
	s_nop 0
	s_nop 0
	v_lshlrev_b32_e32 v60, 16, v42
	v_and_b32_e32 v42, 0xffff0000, v42
	v_mul_f32_e32 v58, 0xbfb8aa3b, v60
	v_mul_f32_e32 v59, 0xbfb8aa3b, v42
	v_exp_f32_e32 v58, v58
	v_exp_f32_e32 v59, v59
	s_nop 0
	v_pk_add_f32 v[58:59], v[58:59], 1.0 op_sel_hi:[1,0]
	s_nop 0
	s_nop 0
	v_rcp_f32_e32 v61, v59
	s_nop 0
	v_mul_f32_e32 v59, v42, v61
	s_nop 0
	v_rcp_f32_e32 v42, v58
	s_nop 0
	v_mul_f32_e32 v58, v60, v42
	v_pk_mul_f32 v[54:55], v[58:59], v[54:55]
	v_lshlrev_b32_e32 v58, 16, v43
	v_and_b32_e32 v43, 0xffff0000, v43
	v_cvt_pk_bf16_f32 v42, v54, v55
	v_mul_f32_e32 v54, 0xbfb8aa3b, v58
	v_mul_f32_e32 v55, 0xbfb8aa3b, v43
	v_exp_f32_e32 v54, v54
	v_exp_f32_e32 v55, v55
	s_nop 0
	v_pk_add_f32 v[54:55], v[54:55], 1.0 op_sel_hi:[1,0]
	s_nop 0
	s_nop 0
	v_rcp_f32_e32 v59, v55
	s_nop 0
	v_mul_f32_e32 v55, v43, v59
	s_nop 0
	v_rcp_f32_e32 v43, v54
	s_nop 0
	v_mul_f32_e32 v54, v58, v43
	v_pk_mul_f32 v[54:55], v[54:55], v[56:57]
	v_lshlrev_b32_e32 v56, 16, v44
	v_and_b32_e32 v44, 0xffff0000, v44
	v_cvt_pk_bf16_f32 v43, v54, v55
	v_mul_f32_e32 v54, 0xbfb8aa3b, v56
	v_mul_f32_e32 v55, 0xbfb8aa3b, v44
	v_exp_f32_e32 v54, v54
	v_exp_f32_e32 v55, v55
	s_nop 0
	v_pk_add_f32 v[54:55], v[54:55], 1.0 op_sel_hi:[1,0]
	s_nop 0
	s_nop 0
	v_rcp_f32_e32 v57, v55
	s_nop 0
	v_mul_f32_e32 v55, v44, v57
	s_nop 0
	v_rcp_f32_e32 v44, v54
	s_nop 0
	v_mul_f32_e32 v54, v56, v44
	v_pk_mul_f32 v[50:51], v[54:55], v[50:51]
	v_lshlrev_b32_e32 v54, 16, v45
	v_and_b32_e32 v45, 0xffff0000, v45
	v_cvt_pk_bf16_f32 v44, v50, v51
	v_mul_f32_e32 v50, 0xbfb8aa3b, v54
	v_mul_f32_e32 v51, 0xbfb8aa3b, v45
	v_exp_f32_e32 v50, v50
	v_exp_f32_e32 v51, v51
	s_nop 0
	v_pk_add_f32 v[50:51], v[50:51], 1.0 op_sel_hi:[1,0]
	s_nop 0
	s_nop 0
	v_rcp_f32_e32 v55, v51
	s_nop 0
	v_mul_f32_e32 v51, v45, v55
	s_nop 0
	v_rcp_f32_e32 v45, v50
	s_nop 0
	v_mul_f32_e32 v50, v54, v45
	v_pk_mul_f32 v[50:51], v[50:51], v[52:53]
	s_nop 0
	v_cvt_pk_bf16_f32 v45, v50, v51
	v_lshlrev_b64 v[50:51], 11, v[80:81]
	v_lshl_add_u64 v[50:51], s[18:19], 0, v[50:51]
	v_lshl_add_u64 v[50:51], v[50:51], 0, v[82:83]
	global_store_dwordx4 v[50:51], v[42:45], off offset:1024
	s_nop 1
	v_pk_mul_f32 v[42:43], v[48:49], s[4:5] op_sel_hi:[1,0]
	v_lshlrev_b32_e32 v48, 16, v34
	v_and_b32_e32 v34, 0xffff0000, v34
	v_pk_mul_f32 v[44:45], v[46:47], s[4:5] op_sel_hi:[1,0]
	v_mul_f32_e32 v46, 0xbfb8aa3b, v48
	v_mul_f32_e32 v47, 0xbfb8aa3b, v34
	v_exp_f32_e32 v46, v46
	v_exp_f32_e32 v47, v47
	s_nop 0
	v_pk_add_f32 v[46:47], v[46:47], 1.0 op_sel_hi:[1,0]
	s_nop 0
	s_nop 0
	v_rcp_f32_e32 v49, v47
	s_nop 0
	v_mul_f32_e32 v47, v34, v49
	s_nop 0
	v_rcp_f32_e32 v34, v46
	s_nop 0
	v_mul_f32_e32 v46, v48, v34
	v_pk_mul_f32 v[44:45], v[46:47], v[44:45]
	v_lshlrev_b32_e32 v46, 16, v35
	v_and_b32_e32 v35, 0xffff0000, v35
	v_cvt_pk_bf16_f32 v34, v44, v45
	v_mul_f32_e32 v44, 0xbfb8aa3b, v46
	v_mul_f32_e32 v45, 0xbfb8aa3b, v35
	v_exp_f32_e32 v44, v44
	v_exp_f32_e32 v45, v45
	s_nop 0
	v_pk_add_f32 v[44:45], v[44:45], 1.0 op_sel_hi:[1,0]
	s_nop 0
	s_nop 0
	v_rcp_f32_e32 v47, v45
	s_nop 0
	v_mul_f32_e32 v45, v35, v47
	s_nop 0
	v_rcp_f32_e32 v35, v44
	s_nop 0
	v_mul_f32_e32 v44, v46, v35
	v_pk_mul_f32 v[42:43], v[44:45], v[42:43]
	v_lshlrev_b32_e32 v44, 16, v36
	v_and_b32_e32 v36, 0xffff0000, v36
	v_cvt_pk_bf16_f32 v35, v42, v43
	v_mul_f32_e32 v42, 0xbfb8aa3b, v44
	v_mul_f32_e32 v43, 0xbfb8aa3b, v36
	v_exp_f32_e32 v42, v42
	v_exp_f32_e32 v43, v43
	s_nop 0
	v_pk_add_f32 v[42:43], v[42:43], 1.0 op_sel_hi:[1,0]
	s_nop 0
	s_nop 0
	v_rcp_f32_e32 v45, v43
	s_nop 0
	v_mul_f32_e32 v43, v36, v45
	s_nop 0
	v_rcp_f32_e32 v36, v42
	s_nop 0
	v_mul_f32_e32 v42, v44, v36
	v_pk_mul_f32 v[38:39], v[42:43], v[38:39]
	v_lshlrev_b32_e32 v42, 16, v37
	v_and_b32_e32 v37, 0xffff0000, v37
	v_cvt_pk_bf16_f32 v36, v38, v39
	v_mul_f32_e32 v38, 0xbfb8aa3b, v42
	v_mul_f32_e32 v39, 0xbfb8aa3b, v37
	v_exp_f32_e32 v38, v38
	v_exp_f32_e32 v39, v39
	s_nop 0
	v_pk_add_f32 v[38:39], v[38:39], 1.0 op_sel_hi:[1,0]
	s_nop 0
	s_nop 0
	v_rcp_f32_e32 v43, v39
	s_nop 0
	v_mul_f32_e32 v39, v37, v43
	s_nop 0
	v_rcp_f32_e32 v37, v38
	s_nop 0
	v_mul_f32_e32 v38, v42, v37
	v_pk_mul_f32 v[38:39], v[38:39], v[40:41]
	s_and_b64 vcc, s[6:7], exec
	v_cvt_pk_bf16_f32 v37, v38, v39
	v_lshlrev_b64 v[38:39], 11, v[78:79]
	v_lshl_add_u64 v[38:39], s[18:19], 0, v[38:39]
	v_lshl_add_u64 v[38:39], v[38:39], 0, v[82:83]
	global_store_dwordx4 v[38:39], v[34:37], off offset:1024
	s_cbranch_vccnz .LBB0_308

.LBB0_311:
	s_nop 0
	v_lshl_add_u64 v[10:11], s[34:35], 0, v[52:53]
	v_add_co_u32_e32 v60, vcc, 0x27000000, v10
	v_lshl_add_u64 v[74:75], s[34:35], 0, v[54:55]
	s_nop 0
	v_addc_co_u32_e32 v61, vcc, 0, v11, vcc
	v_add_co_u32_e32 v72, vcc, 0x2b000000, v10
	global_load_dwordx4 v[46:49], v[60:61], off nt
	s_nop 0
	v_addc_co_u32_e32 v73, vcc, 0, v11, vcc
	global_load_dwordx4 v[56:59], v[72:73], off nt
	global_load_dwordx4 v[68:71], v[74:75], off offset:-256 nt
	global_load_dwordx4 v[42:45], v[60:61], off offset:1024 nt
	global_load_dwordx4 v[38:41], v[72:73], off offset:1024 nt
	global_load_dwordx4 v[34:37], v[74:75], off offset:-128 nt
	global_load_dwordx4 v[30:33], v[60:61], off offset:2048 nt
	global_load_dwordx4 v[26:29], v[72:73], off offset:2048 nt
	global_load_dwordx4 v[22:25], v[74:75], off nt
	global_load_dwordx4 v[18:21], v[60:61], off offset:3072 nt
	global_load_dwordx4 v[14:17], v[72:73], off offset:3072 nt
	global_load_dwordx4 v[10:13], v[74:75], off offset:128 nt
	s_add_i32 s4, s4, s6
	v_lshl_add_u64 v[52:53], v[52:53], 0, s[10:11]
	v_lshl_add_u64 v[54:55], v[54:55], 0, s[12:13]
	s_cmp_lt_i32 s4, 0x10000
	s_waitcnt vmcnt(9)
	v_lshlrev_b32_e32 v67, 16, v70
	v_and_b32_e32 v70, 0xffff0000, v70
	v_lshlrev_b32_e32 v60, 16, v49
	v_and_b32_e32 v61, 0xffff0000, v49
	v_lshlrev_b32_e32 v72, 16, v59
	v_and_b32_e32 v73, 0xffff0000, v59
	v_pk_add_f32 v[60:61], v[60:61], v[72:73]
	v_lshlrev_b32_e32 v72, 16, v48
	v_and_b32_e32 v73, 0xffff0000, v48
	v_lshlrev_b32_e32 v48, 16, v58
	v_and_b32_e32 v49, 0xffff0000, v58
	v_pk_add_f32 v[48:49], v[72:73], v[48:49]
	v_mov_b32_e32 v58, v60
	v_mov_b32_e32 v59, v48
	v_pk_mul_f32 v[58:59], v[58:59], v[58:59]
	v_mov_b32_e32 v72, v61
	v_mov_b32_e32 v73, v49
	v_pk_fma_f32 v[58:59], v[72:73], v[72:73], v[58:59]
	v_mul_f32_e32 v72, 0xbfb8aa3b, v67
	v_mul_f32_e32 v73, 0xbfb8aa3b, v70
	v_exp_f32_e32 v72, v72
	v_exp_f32_e32 v73, v73
	s_nop 0
	v_pk_add_f32 v[72:73], v[72:73], 1.0 op_sel_hi:[1,0]
	s_nop 0
	s_nop 0
	v_rcp_f32_e32 v74, v73
	s_nop 0
	v_mul_f32_e32 v73, v70, v74
	s_nop 0
	v_lshlrev_b32_e32 v74, 16, v47
	v_and_b32_e32 v75, 0xffff0000, v47
	v_lshlrev_b32_e32 v47, 16, v69
	v_rcp_f32_e32 v70, v72
	s_nop 0
	v_mul_f32_e32 v72, v67, v70
	v_lshlrev_b32_e32 v76, 16, v57
	v_and_b32_e32 v77, 0xffff0000, v57
	v_and_b32_e32 v57, 0xffff0000, v69
	v_mul_f32_e32 v67, 0xbfb8aa3b, v47
	v_pk_add_f32 v[74:75], v[74:75], v[76:77]
	v_exp_f32_e32 v76, v67
	v_mul_f32_e32 v67, 0xbfb8aa3b, v57
	v_exp_f32_e32 v77, v67
	s_nop 0
	v_pk_add_f32 v[76:77], v[76:77], 1.0 op_sel_hi:[1,0]
	s_nop 0
	s_nop 0
	v_rcp_f32_e32 v67, v77
	s_nop 0
	v_mul_f32_e32 v77, v57, v67
	v_and_b32_e32 v79, 0xffff0000, v46
	v_rcp_f32_e32 v57, v76
	s_nop 0
	v_mul_f32_e32 v76, v47, v57
	v_lshlrev_b32_e32 v78, 16, v46
	v_lshlrev_b32_e32 v46, 16, v56
	v_and_b32_e32 v47, 0xffff0000, v56
	v_pk_add_f32 v[46:47], v[78:79], v[46:47]
	v_mov_b32_e32 v57, v74
	v_mov_b32_e32 v56, v46
	v_pk_mul_f32 v[56:57], v[56:57], v[56:57]
	v_mov_b32_e32 v78, v47
	v_mov_b32_e32 v79, v75
	v_lshlrev_b32_e32 v67, 16, v68
	v_and_b32_e32 v70, 0xffff0000, v68
	v_pk_fma_f32 v[56:57], v[78:79], v[78:79], v[56:57]
	v_mul_f32_e32 v68, 0xbfb8aa3b, v67
	v_mul_f32_e32 v69, 0xbfb8aa3b, v70
	v_exp_f32_e32 v68, v68
	v_exp_f32_e32 v69, v69
	v_add_f32_e32 v56, v56, v57
	v_add_f32_e32 v56, v59, v56
	v_add_f32_e32 v56, v58, v56
	ds_bpermute_b32 v57, v1, v56
	v_pk_add_f32 v[68:69], v[68:69], 1.0 op_sel_hi:[1,0]
	s_waitcnt lgkmcnt(0)
	v_add_f32_e32 v56, v56, v57
	ds_bpermute_b32 v57, v62, v56
	s_waitcnt lgkmcnt(0)
	v_add_f32_e32 v56, v56, v57
	ds_bpermute_b32 v57, v63, v56
	v_rcp_f32_e32 v78, v69
	s_nop 0
	v_mul_f32_e32 v69, v70, v78
	s_waitcnt lgkmcnt(0)
	v_add_f32_e32 v56, v56, v57
	ds_bpermute_b32 v57, v64, v56
	s_waitcnt lgkmcnt(0)
	v_add_f32_e32 v56, v56, v57
	v_fmamk_f32 v56, v56, 0x3c000000, v65
	v_cmp_gt_f32_e32 vcc, s5, v56
	v_mul_f32_e32 v57, 0x4f800000, v56
	v_rcp_f32_e32 v70, v68
	s_nop 0
	v_mul_f32_e32 v68, v67, v70
	v_cndmask_b32_e32 v56, v56, v57, vcc
	v_sqrt_f32_e32 v57, v56
	s_nop 0
	v_add_u32_e32 v58, -1, v57
	v_fma_f32 v59, -v58, v57, v56
	v_cmp_ge_f32_e64 s[0:1], 0, v59
	v_add_u32_e32 v59, 1, v57
	s_nop 0
	v_cndmask_b32_e64 v58, v57, v58, s[0:1]
	v_fma_f32 v57, -v59, v57, v56
	v_cmp_lt_f32_e64 s[0:1], 0, v57
	s_nop 1
	v_cndmask_b32_e64 v57, v58, v59, s[0:1]
	v_mul_f32_e32 v58, 0x37800000, v57
	v_cndmask_b32_e32 v57, v57, v58, vcc
	v_cmp_class_f32_e32 vcc, v56, v66
	s_nop 1
	v_cndmask_b32_e32 v56, v57, v56, vcc
	s_nop 0
	v_rcp_f32_e32 v56, v56
	s_nop 0
	v_pk_mul_f32 v[48:49], v[48:49], v[56:57] op_sel_hi:[1,0]
	v_pk_mul_f32 v[46:47], v[46:47], v[56:57] op_sel_hi:[1,0]
	v_pk_mul_f32 v[58:59], v[74:75], v[56:57] op_sel_hi:[1,0]
	v_pk_mul_f32 v[48:49], v[6:7], v[48:49]
	v_pk_mul_f32 v[46:47], v[2:3], v[46:47]
	v_pk_mul_f32 v[58:59], v[4:5], v[58:59]
	v_pk_mul_f32 v[48:49], v[72:73], v[48:49]
	v_pk_mul_f32 v[46:47], v[68:69], v[46:47]
	v_pk_mul_f32 v[58:59], v[76:77], v[58:59]
	v_cvt_pk_bf16_f32 v48, v48, v49
	v_lshlrev_b32_e32 v49, 16, v71
	v_and_b32_e32 v67, 0xffff0000, v71
	v_cvt_pk_bf16_f32 v46, v46, v47
	v_cvt_pk_bf16_f32 v47, v58, v59
	v_mul_f32_e32 v57, 0xbfb8aa3b, v49
	v_mul_f32_e32 v59, 0xbfb8aa3b, v67
	v_exp_f32_e32 v58, v57
	v_exp_f32_e32 v59, v59
	v_pk_mul_f32 v[56:57], v[60:61], v[56:57] op_sel_hi:[1,0]
	v_pk_add_f32 v[58:59], v[58:59], 1.0 op_sel_hi:[1,0]
	s_nop 0
	v_pk_mul_f32 v[56:57], v[8:9], v[56:57]
	v_rcp_f32_e32 v60, v59
	s_nop 0
	v_mul_f32_e32 v59, v67, v60
	s_nop 0
	v_rcp_f32_e32 v60, v58
	s_nop 0
	v_mul_f32_e32 v58, v49, v60
	v_pk_mul_f32 v[56:57], v[58:59], v[56:57]
	s_waitcnt vmcnt(6)
	v_lshlrev_b32_e32 v60, 16, v36
	v_cvt_pk_bf16_f32 v49, v56, v57
	v_lshl_add_u64 v[56:57], s[34:35], 0, v[50:51]
	v_add_co_u32_e32 v58, vcc, s7, v56
	v_and_b32_e32 v36, 0xffff0000, v36
	s_nop 0
	v_addc_co_u32_e32 v59, vcc, 0, v57, vcc
	v_add_co_u32_e32 v56, vcc, s14, v56
	v_lshl_add_u64 v[50:51], v[50:51], 0, s[8:9]
	s_nop 0
	v_addc_co_u32_e32 v57, vcc, 0, v57, vcc
	global_store_dwordx4 v[56:57], v[46:49], off offset:-4096
	s_nop 1
	v_lshlrev_b32_e32 v46, 16, v45
	v_and_b32_e32 v47, 0xffff0000, v45
	v_lshlrev_b32_e32 v48, 16, v41
	v_and_b32_e32 v49, 0xffff0000, v41
	v_pk_add_f32 v[46:47], v[46:47], v[48:49]
	v_lshlrev_b32_e32 v48, 16, v44
	v_and_b32_e32 v49, 0xffff0000, v44
	v_lshlrev_b32_e32 v44, 16, v40
	v_and_b32_e32 v45, 0xffff0000, v40
	v_pk_add_f32 v[40:41], v[48:49], v[44:45]
	v_mov_b32_e32 v44, v46
	v_mov_b32_e32 v45, v40
	v_pk_mul_f32 v[44:45], v[44:45], v[44:45]
	v_mov_b32_e32 v48, v47
	v_mov_b32_e32 v49, v41
	v_pk_fma_f32 v[44:45], v[48:49], v[48:49], v[44:45]
	v_mul_f32_e32 v48, 0xbfb8aa3b, v60
	v_mul_f32_e32 v49, 0xbfb8aa3b, v36
	v_exp_f32_e32 v48, v48
	v_exp_f32_e32 v49, v49
	s_nop 0
	v_pk_add_f32 v[48:49], v[48:49], 1.0 op_sel_hi:[1,0]
	s_nop 0
	s_nop 0
	v_rcp_f32_e32 v61, v49
	s_nop 0
	v_mul_f32_e32 v49, v36, v61
	s_nop 0
	v_rcp_f32_e32 v36, v48
	s_nop 0
	v_mul_f32_e32 v48, v60, v36
	v_lshlrev_b32_e32 v36, 16, v35
	v_lshlrev_b32_e32 v60, 16, v43
	v_and_b32_e32 v61, 0xffff0000, v43
	v_lshlrev_b32_e32 v68, 16, v39
	v_and_b32_e32 v69, 0xffff0000, v39
	v_and_b32_e32 v35, 0xffff0000, v35
	v_mul_f32_e32 v39, 0xbfb8aa3b, v36
	v_pk_add_f32 v[60:61], v[60:61], v[68:69]
	v_exp_f32_e32 v68, v39
	v_mul_f32_e32 v39, 0xbfb8aa3b, v35
	v_exp_f32_e32 v69, v39
	s_nop 0
	v_pk_add_f32 v[68:69], v[68:69], 1.0 op_sel_hi:[1,0]
	s_nop 0
	s_nop 0
	v_rcp_f32_e32 v39, v69
	s_nop 0
	v_mul_f32_e32 v69, v35, v39
	v_and_b32_e32 v71, 0xffff0000, v42
	v_rcp_f32_e32 v35, v68
	s_nop 0
	v_mul_f32_e32 v68, v36, v35
	v_lshlrev_b32_e32 v36, 16, v34
	v_and_b32_e32 v67, 0xffff0000, v34
	v_mul_f32_e32 v34, 0xbfb8aa3b, v36
	v_mul_f32_e32 v35, 0xbfb8aa3b, v67
	v_exp_f32_e32 v34, v34
	v_exp_f32_e32 v35, v35
	v_lshlrev_b32_e32 v70, 16, v42
	v_lshlrev_b32_e32 v42, 16, v38
	v_and_b32_e32 v43, 0xffff0000, v38
	v_pk_add_f32 v[42:43], v[70:71], v[42:43]
	v_mov_b32_e32 v39, v60
	v_mov_b32_e32 v38, v42
	v_pk_mul_f32 v[38:39], v[38:39], v[38:39]
	v_mov_b32_e32 v70, v43
	v_mov_b32_e32 v71, v61
	v_pk_add_f32 v[34:35], v[34:35], 1.0 op_sel_hi:[1,0]
	v_pk_fma_f32 v[38:39], v[70:71], v[70:71], v[38:39]
	s_nop 0
	v_rcp_f32_e32 v70, v35
	s_nop 0
	v_mul_f32_e32 v35, v67, v70
	s_nop 0
	v_rcp_f32_e32 v67, v34
	s_nop 0
	v_mul_f32_e32 v34, v36, v67
	v_add_f32_e32 v36, v38, v39
	v_add_f32_e32 v36, v45, v36
	v_add_f32_e32 v36, v44, v36
	ds_bpermute_b32 v38, v1, v36
	s_waitcnt lgkmcnt(0)
	v_add_f32_e32 v36, v36, v38
	ds_bpermute_b32 v38, v62, v36
	s_waitcnt lgkmcnt(0)
	v_add_f32_e32 v36, v36, v38
	ds_bpermute_b32 v38, v63, v36
	s_waitcnt lgkmcnt(0)
	v_add_f32_e32 v36, v36, v38
	ds_bpermute_b32 v38, v64, v36
	s_waitcnt lgkmcnt(0)
	v_add_f32_e32 v36, v36, v38
	v_fmamk_f32 v36, v36, 0x3c000000, v65
	v_cmp_gt_f32_e32 vcc, s5, v36
	v_mul_f32_e32 v38, 0x4f800000, v36
	s_nop 0
	v_cndmask_b32_e32 v36, v36, v38, vcc
	v_sqrt_f32_e32 v38, v36
	s_nop 0
	v_add_u32_e32 v39, -1, v38
	v_fma_f32 v44, -v39, v38, v36
	v_cmp_ge_f32_e64 s[0:1], 0, v44
	v_add_u32_e32 v44, 1, v38
	s_nop 0
	v_cndmask_b32_e64 v39, v38, v39, s[0:1]
	v_fma_f32 v38, -v44, v38, v36
	v_cmp_lt_f32_e64 s[0:1], 0, v38
	s_nop 1
	v_cndmask_b32_e64 v38, v39, v44, s[0:1]
	v_mul_f32_e32 v39, 0x37800000, v38
	v_cndmask_b32_e32 v38, v38, v39, vcc
	v_cmp_class_f32_e32 vcc, v36, v66
	s_nop 1
	v_cndmask_b32_e32 v36, v38, v36, vcc
	s_nop 0
	v_rcp_f32_e32 v38, v36
	s_nop 0
	v_pk_mul_f32 v[42:43], v[42:43], v[38:39] op_sel_hi:[1,0]
	v_pk_mul_f32 v[40:41], v[40:41], v[38:39] op_sel_hi:[1,0]
	v_pk_mul_f32 v[42:43], v[2:3], v[42:43]
	v_pk_mul_f32 v[40:41], v[6:7], v[40:41]
	v_pk_mul_f32 v[34:35], v[34:35], v[42:43]
	v_pk_mul_f32 v[42:43], v[60:61], v[38:39] op_sel_hi:[1,0]
	v_cvt_pk_bf16_f32 v34, v34, v35
	v_pk_mul_f32 v[42:43], v[4:5], v[42:43]
	v_pk_mul_f32 v[40:41], v[48:49], v[40:41]
	v_pk_mul_f32 v[42:43], v[68:69], v[42:43]
	v_cvt_pk_bf16_f32 v36, v40, v41
	v_cvt_pk_bf16_f32 v35, v42, v43
	v_lshlrev_b32_e32 v42, 16, v37
	v_and_b32_e32 v37, 0xffff0000, v37
	v_mul_f32_e32 v39, 0xbfb8aa3b, v42
	v_mul_f32_e32 v41, 0xbfb8aa3b, v37
	v_exp_f32_e32 v40, v39
	v_exp_f32_e32 v41, v41
	v_pk_mul_f32 v[38:39], v[46:47], v[38:39] op_sel_hi:[1,0]
	v_pk_add_f32 v[40:41], v[40:41], 1.0 op_sel_hi:[1,0]
	s_nop 0
	v_pk_mul_f32 v[38:39], v[8:9], v[38:39]
	v_rcp_f32_e32 v43, v41
	s_nop 0
	v_mul_f32_e32 v41, v37, v43
	s_nop 0
	v_rcp_f32_e32 v37, v40
	s_nop 0
	v_mul_f32_e32 v40, v42, v37
	v_pk_mul_f32 v[38:39], v[40:41], v[38:39]
	s_nop 0
	v_cvt_pk_bf16_f32 v37, v38, v39
	global_store_dwordx4 v[58:59], v[34:37], off offset:2048
	s_waitcnt vmcnt(5)
	v_lshlrev_b32_e32 v38, 16, v24
	v_and_b32_e32 v24, 0xffff0000, v24
	v_lshlrev_b32_e32 v34, 16, v33
	v_and_b32_e32 v35, 0xffff0000, v33
	v_lshlrev_b32_e32 v36, 16, v29
	v_and_b32_e32 v37, 0xffff0000, v29
	v_pk_add_f32 v[34:35], v[34:35], v[36:37]
	v_lshlrev_b32_e32 v36, 16, v32
	v_and_b32_e32 v37, 0xffff0000, v32
	v_lshlrev_b32_e32 v32, 16, v28
	v_and_b32_e32 v33, 0xffff0000, v28
	v_pk_add_f32 v[28:29], v[36:37], v[32:33]
	v_mov_b32_e32 v32, v34
	v_mov_b32_e32 v33, v28
	v_pk_mul_f32 v[32:33], v[32:33], v[32:33]
	v_mov_b32_e32 v36, v35
	v_mov_b32_e32 v37, v29
	v_pk_fma_f32 v[32:33], v[36:37], v[36:37], v[32:33]
	v_mul_f32_e32 v36, 0xbfb8aa3b, v38
	v_mul_f32_e32 v37, 0xbfb8aa3b, v24
	v_exp_f32_e32 v36, v36
	v_exp_f32_e32 v37, v37
	s_nop 0
	v_pk_add_f32 v[36:37], v[36:37], 1.0 op_sel_hi:[1,0]
	s_nop 0
	s_nop 0
	v_rcp_f32_e32 v39, v37
	s_nop 0
	v_mul_f32_e32 v37, v24, v39
	s_nop 0
	v_rcp_f32_e32 v24, v36
	s_nop 0
	v_mul_f32_e32 v36, v38, v24
	v_lshlrev_b32_e32 v24, 16, v23
	v_lshlrev_b32_e32 v38, 16, v31
	v_and_b32_e32 v39, 0xffff0000, v31
	v_lshlrev_b32_e32 v40, 16, v27
	v_and_b32_e32 v41, 0xffff0000, v27
	v_and_b32_e32 v23, 0xffff0000, v23
	v_mul_f32_e32 v27, 0xbfb8aa3b, v24
	v_pk_add_f32 v[38:39], v[38:39], v[40:41]
	v_exp_f32_e32 v40, v27
	v_mul_f32_e32 v27, 0xbfb8aa3b, v23
	v_exp_f32_e32 v41, v27
	s_nop 0
	v_pk_add_f32 v[40:41], v[40:41], 1.0 op_sel_hi:[1,0]
	s_nop 0
	s_nop 0
	v_rcp_f32_e32 v27, v41
	s_nop 0
	v_mul_f32_e32 v41, v23, v27
	s_nop 0
	v_lshlrev_b32_e32 v42, 16, v30
	v_and_b32_e32 v43, 0xffff0000, v30
	v_lshlrev_b32_e32 v30, 16, v26
	v_and_b32_e32 v31, 0xffff0000, v26
	v_pk_add_f32 v[30:31], v[42:43], v[30:31]
	v_mov_b32_e32 v27, v38
	v_mov_b32_e32 v26, v30
	v_pk_mul_f32 v[26:27], v[26:27], v[26:27]
	v_mov_b32_e32 v42, v31
	v_mov_b32_e32 v43, v39
	v_rcp_f32_e32 v23, v40
	s_nop 0
	v_mul_f32_e32 v40, v24, v23
	v_pk_fma_f32 v[26:27], v[42:43], v[42:43], v[26:27]
	v_lshlrev_b32_e32 v24, 16, v22
	v_and_b32_e32 v42, 0xffff0000, v22
	v_mul_f32_e32 v22, 0xbfb8aa3b, v24
	v_mul_f32_e32 v23, 0xbfb8aa3b, v42
	v_exp_f32_e32 v22, v22
	v_exp_f32_e32 v23, v23
	s_nop 0
	v_pk_add_f32 v[22:23], v[22:23], 1.0 op_sel_hi:[1,0]
	s_nop 0
	s_nop 0
	v_rcp_f32_e32 v43, v23
	s_nop 0
	v_mul_f32_e32 v23, v42, v43
	s_nop 0
	v_rcp_f32_e32 v42, v22
	s_nop 0
	v_mul_f32_e32 v22, v24, v42
	v_add_f32_e32 v24, v26, v27
	v_add_f32_e32 v24, v33, v24
	v_add_f32_e32 v24, v32, v24
	ds_bpermute_b32 v26, v1, v24
	s_waitcnt lgkmcnt(0)
	v_add_f32_e32 v24, v24, v26
	ds_bpermute_b32 v26, v62, v24
	s_waitcnt lgkmcnt(0)
	v_add_f32_e32 v24, v24, v26
	ds_bpermute_b32 v26, v63, v24
	s_waitcnt lgkmcnt(0)
	v_add_f32_e32 v24, v24, v26
	ds_bpermute_b32 v26, v64, v24
	s_waitcnt lgkmcnt(0)
	v_add_f32_e32 v24, v24, v26
	v_fmamk_f32 v24, v24, 0x3c000000, v65
	v_cmp_gt_f32_e32 vcc, s5, v24
	v_mul_f32_e32 v26, 0x4f800000, v24
	s_nop 0
	v_cndmask_b32_e32 v24, v24, v26, vcc
	v_sqrt_f32_e32 v26, v24
	s_nop 0
	v_add_u32_e32 v27, -1, v26
	v_fma_f32 v32, -v27, v26, v24
	v_cmp_ge_f32_e64 s[0:1], 0, v32
	v_add_u32_e32 v32, 1, v26
	s_nop 0
	v_cndmask_b32_e64 v27, v26, v27, s[0:1]
	v_fma_f32 v26, -v32, v26, v24
	v_cmp_lt_f32_e64 s[0:1], 0, v26
	s_nop 1
	v_cndmask_b32_e64 v26, v27, v32, s[0:1]
	v_mul_f32_e32 v27, 0x37800000, v26
	v_cndmask_b32_e32 v26, v26, v27, vcc
	v_cmp_class_f32_e32 vcc, v24, v66
	s_nop 1
	v_cndmask_b32_e32 v24, v26, v24, vcc
	s_nop 0
	v_rcp_f32_e32 v26, v24
	s_nop 0
	v_pk_mul_f32 v[30:31], v[30:31], v[26:27] op_sel_hi:[1,0]
	v_pk_mul_f32 v[28:29], v[28:29], v[26:27] op_sel_hi:[1,0]
	v_pk_mul_f32 v[30:31], v[2:3], v[30:31]
	v_pk_mul_f32 v[28:29], v[6:7], v[28:29]
	v_pk_mul_f32 v[22:23], v[22:23], v[30:31]
	v_pk_mul_f32 v[30:31], v[38:39], v[26:27] op_sel_hi:[1,0]
	v_cvt_pk_bf16_f32 v22, v22, v23
	v_pk_mul_f32 v[30:31], v[4:5], v[30:31]
	v_pk_mul_f32 v[28:29], v[36:37], v[28:29]
	v_pk_mul_f32 v[30:31], v[40:41], v[30:31]
	v_cvt_pk_bf16_f32 v24, v28, v29
	v_cvt_pk_bf16_f32 v23, v30, v31
	v_lshlrev_b32_e32 v30, 16, v25
	v_and_b32_e32 v25, 0xffff0000, v25
	v_mul_f32_e32 v27, 0xbfb8aa3b, v30
	v_mul_f32_e32 v29, 0xbfb8aa3b, v25
	v_exp_f32_e32 v28, v27
	v_exp_f32_e32 v29, v29
	v_pk_mul_f32 v[26:27], v[34:35], v[26:27] op_sel_hi:[1,0]
	v_pk_add_f32 v[28:29], v[28:29], 1.0 op_sel_hi:[1,0]
	s_nop 0
	v_pk_mul_f32 v[26:27], v[8:9], v[26:27]
	v_rcp_f32_e32 v31, v29
	s_nop 0
	v_mul_f32_e32 v29, v25, v31
	s_nop 0
	v_rcp_f32_e32 v25, v28
	s_nop 0
	v_mul_f32_e32 v28, v30, v25
	v_pk_mul_f32 v[26:27], v[28:29], v[26:27]
	s_nop 0
	v_cvt_pk_bf16_f32 v25, v26, v27
	global_store_dwordx4 v[56:57], v[22:25], off
	s_waitcnt vmcnt(3)
	v_lshlrev_b32_e32 v26, 16, v12
	v_and_b32_e32 v12, 0xffff0000, v12
	v_lshlrev_b32_e32 v22, 16, v21
	v_and_b32_e32 v23, 0xffff0000, v21
	v_lshlrev_b32_e32 v24, 16, v17
	v_and_b32_e32 v25, 0xffff0000, v17
	v_pk_add_f32 v[22:23], v[22:23], v[24:25]
	v_lshlrev_b32_e32 v24, 16, v20
	v_and_b32_e32 v25, 0xffff0000, v20
	v_lshlrev_b32_e32 v20, 16, v16
	v_and_b32_e32 v21, 0xffff0000, v16
	v_pk_add_f32 v[16:17], v[24:25], v[20:21]
	v_mov_b32_e32 v20, v22
	v_mov_b32_e32 v21, v16
	v_pk_mul_f32 v[20:21], v[20:21], v[20:21]
	v_mov_b32_e32 v24, v23
	v_mov_b32_e32 v25, v17
	v_pk_fma_f32 v[20:21], v[24:25], v[24:25], v[20:21]
	v_mul_f32_e32 v24, 0xbfb8aa3b, v26
	v_mul_f32_e32 v25, 0xbfb8aa3b, v12
	v_exp_f32_e32 v24, v24
	v_exp_f32_e32 v25, v25
	s_nop 0
	v_pk_add_f32 v[24:25], v[24:25], 1.0 op_sel_hi:[1,0]
	s_nop 0
	s_nop 0
	v_rcp_f32_e32 v27, v25
	s_nop 0
	v_mul_f32_e32 v25, v12, v27
	s_nop 0
	v_rcp_f32_e32 v12, v24
	s_nop 0
	v_mul_f32_e32 v24, v26, v12
	v_lshlrev_b32_e32 v12, 16, v11
	v_lshlrev_b32_e32 v26, 16, v19
	v_and_b32_e32 v27, 0xffff0000, v19
	v_lshlrev_b32_e32 v28, 16, v15
	v_and_b32_e32 v29, 0xffff0000, v15
	v_and_b32_e32 v11, 0xffff0000, v11
	v_mul_f32_e32 v15, 0xbfb8aa3b, v12
	v_pk_add_f32 v[26:27], v[26:27], v[28:29]
	v_exp_f32_e32 v28, v15
	v_mul_f32_e32 v15, 0xbfb8aa3b, v11
	v_exp_f32_e32 v29, v15
	s_nop 0
	v_pk_add_f32 v[28:29], v[28:29], 1.0 op_sel_hi:[1,0]
	s_nop 0
	s_nop 0
	v_rcp_f32_e32 v15, v29
	s_nop 0
	v_mul_f32_e32 v29, v11, v15
	s_nop 0
	v_lshlrev_b32_e32 v30, 16, v18
	v_and_b32_e32 v31, 0xffff0000, v18
	v_lshlrev_b32_e32 v18, 16, v14
	v_and_b32_e32 v19, 0xffff0000, v14
	v_pk_add_f32 v[18:19], v[30:31], v[18:19]
	v_mov_b32_e32 v15, v26
	v_mov_b32_e32 v14, v18
	v_pk_mul_f32 v[14:15], v[14:15], v[14:15]
	v_mov_b32_e32 v30, v19
	v_mov_b32_e32 v31, v27
	v_rcp_f32_e32 v11, v28
	s_nop 0
	v_mul_f32_e32 v28, v12, v11
	v_pk_fma_f32 v[14:15], v[30:31], v[30:31], v[14:15]
	v_lshlrev_b32_e32 v12, 16, v10
	v_and_b32_e32 v30, 0xffff0000, v10
	v_mul_f32_e32 v10, 0xbfb8aa3b, v12
	v_mul_f32_e32 v11, 0xbfb8aa3b, v30
	v_exp_f32_e32 v10, v10
	v_exp_f32_e32 v11, v11
	s_nop 0
	v_pk_add_f32 v[10:11], v[10:11], 1.0 op_sel_hi:[1,0]
	s_nop 0
	s_nop 0
	v_rcp_f32_e32 v31, v11
	s_nop 0
	v_mul_f32_e32 v11, v30, v31
	s_nop 0
	v_rcp_f32_e32 v30, v10
	s_nop 0
	v_mul_f32_e32 v10, v12, v30
	v_add_f32_e32 v12, v14, v15
	v_add_f32_e32 v12, v21, v12
	v_add_f32_e32 v12, v20, v12
	ds_bpermute_b32 v14, v1, v12
	s_waitcnt lgkmcnt(0)
	v_add_f32_e32 v12, v12, v14
	ds_bpermute_b32 v14, v62, v12
	s_waitcnt lgkmcnt(0)
	v_add_f32_e32 v12, v12, v14
	ds_bpermute_b32 v14, v63, v12
	s_waitcnt lgkmcnt(0)
	v_add_f32_e32 v12, v12, v14
	ds_bpermute_b32 v14, v64, v12
	s_waitcnt lgkmcnt(0)
	v_add_f32_e32 v12, v12, v14
	v_fmamk_f32 v12, v12, 0x3c000000, v65
	v_cmp_gt_f32_e32 vcc, s5, v12
	v_mul_f32_e32 v14, 0x4f800000, v12
	s_nop 0
	v_cndmask_b32_e32 v12, v12, v14, vcc
	v_sqrt_f32_e32 v14, v12
	s_nop 0
	v_add_u32_e32 v15, -1, v14
	v_fma_f32 v20, -v15, v14, v12
	v_cmp_ge_f32_e64 s[0:1], 0, v20
	v_add_u32_e32 v20, 1, v14
	s_nop 0
	v_cndmask_b32_e64 v15, v14, v15, s[0:1]
	v_fma_f32 v14, -v20, v14, v12
	v_cmp_lt_f32_e64 s[0:1], 0, v14
	s_nop 1
	v_cndmask_b32_e64 v14, v15, v20, s[0:1]
	v_mul_f32_e32 v15, 0x37800000, v14
	v_cndmask_b32_e32 v14, v14, v15, vcc
	v_cmp_class_f32_e32 vcc, v12, v66
	s_nop 1
	v_cndmask_b32_e32 v12, v14, v12, vcc
	s_nop 0
	v_rcp_f32_e32 v14, v12
	s_nop 0
	v_pk_mul_f32 v[18:19], v[18:19], v[14:15] op_sel_hi:[1,0]
	v_pk_mul_f32 v[16:17], v[16:17], v[14:15] op_sel_hi:[1,0]
	v_pk_mul_f32 v[18:19], v[2:3], v[18:19]
	v_pk_mul_f32 v[16:17], v[6:7], v[16:17]
	v_pk_mul_f32 v[10:11], v[10:11], v[18:19]
	v_pk_mul_f32 v[18:19], v[26:27], v[14:15] op_sel_hi:[1,0]
	v_cvt_pk_bf16_f32 v10, v10, v11
	v_pk_mul_f32 v[18:19], v[4:5], v[18:19]
	v_pk_mul_f32 v[16:17], v[24:25], v[16:17]
	v_pk_mul_f32 v[18:19], v[28:29], v[18:19]
	v_cvt_pk_bf16_f32 v12, v16, v17
	v_cvt_pk_bf16_f32 v11, v18, v19
	v_lshlrev_b32_e32 v18, 16, v13
	v_and_b32_e32 v13, 0xffff0000, v13
	v_mul_f32_e32 v15, 0xbfb8aa3b, v18
	v_mul_f32_e32 v17, 0xbfb8aa3b, v13
	v_exp_f32_e32 v16, v15
	v_exp_f32_e32 v17, v17
	v_pk_mul_f32 v[14:15], v[22:23], v[14:15] op_sel_hi:[1,0]
	v_pk_add_f32 v[16:17], v[16:17], 1.0 op_sel_hi:[1,0]
	s_nop 0
	v_pk_mul_f32 v[14:15], v[8:9], v[14:15]
	v_rcp_f32_e32 v19, v17
	s_nop 0
	v_mul_f32_e32 v17, v13, v19
	s_nop 0
	v_rcp_f32_e32 v13, v16
	s_nop 0
	v_mul_f32_e32 v16, v18, v13
	v_pk_mul_f32 v[14:15], v[16:17], v[14:15]
	s_nop 0
	v_cvt_pk_bf16_f32 v13, v14, v15
	global_store_dwordx4 v[56:57], v[10:13], off offset:2048
	s_cbranch_scc1 .LBB0_311
